# hoist epilogue-start slot/conv-weight loads to unit start (w_in, w_up)
# baseline (speedup 1.0000x reference)
; __device__ __forceinline__ float row_rstd(const float* slots, int row, int ncols, float eps) { const f32x4 v = *(const f32x4*)(slots + (size_t)row * 4); return rsqrtf(((v[0] + v[1]) + (v[2] + v[3])) * (1.0f / ncols) + eps); }
;     __device__ __forceinline__ void operator()(const f32x4 (&acc)[2][2][4][2], const Unit& u, int wr, int wc, int fr, int fq) const {
;     ...
;           if (tix < 256) xch[2048 + tix] = use_rs ? row_rstd(slots, u.pm * BM + tix, 1024, 1e-6f) : 1.0f;
; template <class Epi, class Sched, bool ALIGN_EPI = false, bool SP2 = false>
; __device__ __forceinline__ void gemm_phase(PG8_LAS unsigned char* lds, const Gemm g, const Sched& S, const Epi& E, const int tid) {
;     ...
;         const bool has_next = S.next(ui + 1, nxt);
;         const char* nA = has_next ? (const char*)g.A + (size_t)nxt.pm * tstepA : cA; const char* nB = has_next ? (const char*)g.Bt + (size_t)nxt.pn * tstep : cB;
.LBB0_87:
	s_lshl_b32 s98, s50, 8
	v_readlane_b32 s100, v252, 34
	v_readlane_b32 s101, v252, 35
	v_add_u32_e32 v244, s98, v159
	v_ashrrev_i32_e32 v245, 31, v244
	s_nop 1
	v_lshl_add_u64 v[244:245], v[244:245], 4, s[100:101]
	s_and_saveexec_b64 s[98:99], s[2:3]
	global_load_dwordx4 v[244:247], v[244:245], off
	s_mov_b64 exec, s[98:99]
	s_add_i32 s66, s66, 1
	s_mul_i32 s0, s66, s67
	s_mul_hi_u32 s1, s66, s87
	s_add_i32 s1, s1, s0
	s_mul_i32 s0, s66, s87
	s_add_u32 s46, s0, s86
	s_addc_u32 s47, s1, s68
	v_mov_b64_e32 v[6:7], 0x400
	v_cmp_lt_i64_e64 s[6:7], s[46:47], v[6:7]
	v_mov_b64_e32 v[6:7], 0x3ff
	v_cmp_gt_i64_e32 vcc, s[46:47], v[6:7]
	s_cbranch_vccnz .LBB0_93
	s_ashr_i32 s0, s46, 31
	s_lshr_b32 s0, s0, 29
	s_add_i32 s0, s46, s0
	s_and_b32 s1, s0, -8
	s_sub_i32 s1, s46, s1
	s_cmp_gt_i32 s1, -1
	s_mov_b64 s[42:43], -1
	s_cbranch_scc0 .LBB0_90
	s_lshl_b32 s9, s1, 7
	s_mov_b64 s[42:43], 0

; __device__ __forceinline__ float row_rstd(const float* slots, int row, int ncols, float eps) { const f32x4 v = *(const f32x4*)(slots + (size_t)row * 4); return rsqrtf(((v[0] + v[1]) + (v[2] + v[3])) * (1.0f / ncols) + eps); }
;     __device__ __forceinline__ void operator()(const f32x4 (&acc)[2][2][4][2], const Unit& u, int wr, int wc, int fr, int fq) const {
;     ...
;         { const int tix = (wr * 4 + wc) * 64 + fq * 16 + fr;
;           if (tix < 256) xch[2048 + tix] = use_rs ? row_rstd(slots, u.pm * BM + tix, 1024, 1e-6f) : 1.0f;
;           asm volatile("s_waitcnt lgkmcnt(0)" ::: "memory"); __builtin_amdgcn_s_barrier(); asm volatile("" ::: "memory"); }
.LBB0_106:
	v_readlane_b32 s18, v252, 34
	v_readlane_b32 s19, v252, 35
	s_mov_b32 s9, 0x800000
	s_nop 0
	v_add_f32_e32 v134, v245, v244
	v_add_f32_e32 v135, v246, v247
	s_nop 0
	v_add_f32_e32 v134, v134, v135
	v_mov_b32_e32 v135, 0x358637bd
	v_fmamk_f32 v134, v134, 0x3a800000, v135
	v_mul_f32_e32 v135, 0x4b800000, v134
	v_cmp_gt_f32_e32 vcc, s9, v134
	s_nop 1
	v_cndmask_b32_e32 v134, v134, v135, vcc
	v_rsq_f32_e32 v134, v134
	s_nop 0
	v_mul_f32_e32 v135, 0x45800000, v134
	v_cndmask_b32_e32 v134, v134, v135, vcc
	ds_write_b32 v178, v134 offset:8192

;     __host__ __device__ bool next(int i, Unit& u) const {
;         const long L = (long)i * G + c; if (L >= nwg) return false;
;         int wgid = (int)L; { const int q = nwg / NXCD, r = nwg % NXCD, xcd = wgid % NXCD, off = wgid / NXCD; wgid = (xcd < r ? xcd * (q + 1) : r * (q + 1) + (xcd - r) * q) + off; }
; template <class Epi, class Sched, bool ALIGN_EPI = false, bool SP2 = false>
; __device__ __forceinline__ void gemm_phase(PG8_LAS unsigned char* lds, const Gemm g, const Sched& S, const Epi& E, const int tid) {
;     ...
;         const bool has_next = S.next(ui + 1, nxt);
.LBB0_489:
	s_add_i32 s56, s56, 1
	s_mul_i32 s0, s56, s57
	s_mul_hi_u32 s1, s56, s87
	s_add_i32 s1, s1, s0
	s_mul_i32 s0, s56, s87
	s_add_u32 s36, s0, s86
	s_addc_u32 s37, s1, s58
	s_waitcnt lgkmcnt(0)
	v_mov_b64_e32 v[6:7], 0x100
	v_mov_b64_e32 v[162:163], 0xff
	v_cmp_gt_i64_e32 vcc, s[36:37], v[162:163]
	v_cmp_lt_i64_e64 s[6:7], s[36:37], v[6:7]
	s_cbranch_vccnz .LBB0_495
	s_ashr_i32 s0, s36, 31
	s_lshr_b32 s0, s0, 29
	s_add_i32 s0, s36, s0
	s_and_b32 s1, s0, -8
	s_sub_i32 s1, s36, s1
	s_cmp_gt_i32 s1, -1
	s_mov_b64 s[12:13], -1
	s_cbranch_scc0 .LBB0_492
	s_lshl_b32 s14, s1, 5
	s_mov_b64 s[12:13], 0

; __device__ __forceinline__ float row_rstd(const float* slots, int row, int ncols, float eps) { const f32x4 v = *(const f32x4*)(slots + (size_t)row * 4); return rsqrtf(((v[0] + v[1]) + (v[2] + v[3])) * (1.0f / ncols) + eps); }
;     __device__ __forceinline__ void operator()(const f32x4 (&acc_)[2][2][4][2], const Unit& u, int wr, int wc, int fr, int fq) const {
;     ...
;         { const int tix = (wr * 4 + wc) * 64 + fq * 16 + fr, wi = tix >> 7, ci = tix & 127;
;           xg[1024 + tix] = wi < 3 ? cw[wi * dff + u.pn * 128 + ci] : cb[u.pn * 128 + ci];
;           if (tix < 256) { int t = a_tok0(u.pm) + tix; t = t < 0 ? 0 : (t > Mtok - 1 ? Mtok - 1 : t); xg[1536 + tix] = row_rstd(slots, t, 1024, 1e-6f); } }
; template <class Epi, class Sched, bool ALIGN_EPI = false, bool SP2 = false>
; __device__ __forceinline__ void gemm_phase(PG8_LAS unsigned char* lds, const Gemm g, const Sched& S, const Epi& E, const int tid) {
;     ...
;         const bool has_next = S.next(ui + 1, nxt);
;         const char* nA = has_next ? (const char*)g.A + (size_t)nxt.pm * tstepA : cA; const char* nB = has_next ? (const char*)g.Bt + (size_t)nxt.pn * tstep : cB;
.LBB0_632:
	s_lshl_b32 s98, s82, 7
	s_mul_i32 s99, s0, 0xfe
	s_add_i32 s99, s99, -1
	v_readlane_b32 s100, v252, 36
	v_readlane_b32 s101, v252, 37
	v_or_b32_e32 v162, s98, v220
	v_add_u32_e32 v163, s98, v230
	v_cndmask_b32_e64 v162, v162, v163, s[2:3]
	v_ashrrev_i32_e32 v163, 31, v162
	v_lshl_add_u64 v[162:163], v[162:163], 2, s[52:53]
	global_load_dword v4, v[162:163], off
	v_add_u32_e32 v216, s99, v219
	v_mov_b32_e32 v217, 0x3fff
	v_med3_i32 v216, v216, 0, v217
	v_lshlrev_b32_e32 v216, 4, v216
	s_and_saveexec_b64 s[98:99], s[4:5]
	global_load_dwordx2 v[162:163], v216, s[100:101]
	global_load_dwordx2 v[216:217], v216, s[100:101] offset:8
	s_mov_b64 exec, s[98:99]
	s_add_i32 s80, s80, 1
	s_mul_i32 s1, s80, s75
	s_mul_hi_u32 s18, s80, s87
	s_add_i32 s18, s18, s1
	s_mul_i32 s1, s80, s87
	s_add_u32 s42, s1, s86
	s_addc_u32 s43, s18, s76
	v_mov_b64_e32 v[6:7], 0x596
	v_cmp_lt_i64_e64 s[44:45], s[42:43], v[6:7]
	v_mov_b64_e32 v[6:7], 0x595
	v_cmp_gt_i64_e32 vcc, s[42:43], v[6:7]
	s_cbranch_vccnz .LBB0_638
	s_ashr_i32 s1, s42, 31
	s_lshr_b32 s1, s1, 29
	s_add_i32 s1, s42, s1
	s_and_b32 s18, s1, -8
	s_sub_i32 s18, s42, s18
	s_cmp_gt_i32 s18, 5
	s_mov_b64 s[42:43], -1
	s_cbranch_scc0 .LBB0_635
	s_mul_i32 s19, s18, 0xb2
	s_add_i32 s19, s19, 6
	s_mov_b64 s[42:43], 0

; __device__ __forceinline__ float row_rstd(const float* slots, int row, int ncols, float eps) { const f32x4 v = *(const f32x4*)(slots + (size_t)row * 4); return rsqrtf(((v[0] + v[1]) + (v[2] + v[3])) * (1.0f / ncols) + eps); }
;     __device__ __forceinline__ void operator()(const f32x4 (&acc_)[2][2][4][2], const Unit& u, int wr, int wc, int fr, int fq) const {
;     ...
;         { const int tix = (wr * 4 + wc) * 64 + fq * 16 + fr, wi = tix >> 7, ci = tix & 127;
;           xg[1024 + tix] = wi < 3 ? cw[wi * dff + u.pn * 128 + ci] : cb[u.pn * 128 + ci];
;           if (tix < 256) { int t = a_tok0(u.pm) + tix; t = t < 0 ? 0 : (t > Mtok - 1 ? Mtok - 1 : t); xg[1536 + tix] = row_rstd(slots, t, 1024, 1e-6f); } }
.LBB0_655:
	s_or_b64 exec, exec, s[44:45]
	s_lshl_b32 s1, s82, 7
	s_mul_i32 s33, s0, 0xfe
	s_add_i32 s33, s33, -1
	ds_write_b32 v231, v4 offset:4096
	s_and_saveexec_b64 s[44:45], s[4:5]
	s_cbranch_execz .LBB0_657
	s_mov_b32 s0, 0x800000
	v_add_f32_e32 v46, v163, v162
	v_add_f32_e32 v47, v216, v217
	s_nop 0
	v_add_f32_e32 v46, v46, v47
	v_mov_b32_e32 v47, 0x358637bd
	v_fmamk_f32 v46, v46, 0x3a800000, v47
	v_mul_f32_e32 v47, 0x4b800000, v46
	v_cmp_gt_f32_e32 vcc, s0, v46
	s_nop 1
	v_cndmask_b32_e32 v46, v46, v47, vcc
	v_rsq_f32_e32 v46, v46
	s_nop 0
	v_mul_f32_e32 v47, 0x45800000, v46
	v_cndmask_b32_e32 v46, v46, v47, vcc
	ds_write_b32 v231, v46 offset:6144

; #define GSYNC() xcd_barrier(xbar)
; DI void xcd_barrier(const XcdBarrier& b) {
;     asm volatile("s_waitcnt vmcnt(0)" ::: "memory");
;     __syncthreads();
;     if (threadIdx.x == 0) {
;         unsigned* bar = b.bar;
;         __builtin_amdgcn_s_waitcnt(0);
;         unsigned nloc = b.st[0], nx = b.st[1];
;         if (nloc == 0u) { xcd_barrier_complete(bar, b.x, nloc, nx); b.st[0] = nloc; b.st[1] = nx; }
; __global__ void __launch_bounds__(NT, 2) mega_fwd(Ctx c) {
;     ...
;             GSYNC();
.LBB0_685:
	v_mov_b32_e32 v4, 1.0
	v_mov_b32_e32 v217, 0xf149f2ca
	v_mbcnt_lo_u32_b32 v216, -1, 0
	v_mbcnt_hi_u32_b32 v216, -1, v216
	s_waitcnt vmcnt(0)
	s_barrier
	s_and_saveexec_b64 s[0:1], s[90:91]
	v_readlane_b32 s82, v254, 22
	s_xor_b64 s[2:3], exec, s[0:1]
	v_readlane_b32 s83, v254, 23
	s_cbranch_execz .LBB0_738
	v_readlane_b32 s0, v253, 60
	s_waitcnt vmcnt(0) expcnt(0) lgkmcnt(0)
	s_nop 0
	v_mov_b32_e32 v1, s0
	ds_read_b32 v3, v1
	v_readlane_b32 s0, v253, 61
	s_waitcnt lgkmcnt(0)
	v_cmp_ne_u32_e32 vcc, 0, v3
	v_mov_b32_e32 v1, s0
	ds_read_b32 v2, v1
	s_cbranch_vccnz .LBB0_701
	s_mov_b32 s0, 1
	s_branch .LBB0_689

;     __host__ __device__ bool next(int i, Unit& u) const {
;         const long L = (long)i * G + c; if (L >= nwg) return false;
;         int wgid = (int)L; { const int q = nwg / NXCD, r = nwg % NXCD, xcd = wgid % NXCD, off = wgid / NXCD; wgid = (xcd < r ? xcd * (q + 1) : r * (q + 1) + (xcd - r) * q) + off; }
; template <class Epi, class Sched, bool ALIGN_EPI = false, bool SP2 = false>
; __device__ __forceinline__ void gemm_phase(PG8_LAS unsigned char* lds, const Gemm g, const Sched& S, const Epi& E, const int tid) {
;     ...
;         const bool has_next = S.next(ui + 1, nxt);
.LBB0_749:
	s_add_i32 s48, s48, 1
	s_mul_i32 s2, s48, s47
	s_mul_hi_u32 s3, s48, s87
	s_add_i32 s3, s3, s2
	s_mul_i32 s2, s48, s87
	s_add_u32 s2, s2, s86
	s_addc_u32 s3, s3, s20
	v_mov_b64_e32 v[6:7], 0x100
	v_mov_b64_e32 v[162:163], 0xff
	v_cmp_gt_i64_e32 vcc, s[2:3], v[162:163]
	v_cmp_lt_i64_e64 s[4:5], s[2:3], v[6:7]
	s_cbranch_vccnz .LBB0_755
	s_ashr_i32 s3, s2, 31
	s_lshr_b32 s3, s3, 29
	s_add_i32 s10, s2, s3
	s_and_b32 s3, s10, -8
	s_sub_i32 s11, s2, s3
	s_cmp_gt_i32 s11, -1
	s_mov_b64 s[2:3], -1
	s_cbranch_scc0 .LBB0_752
	s_lshl_b32 s18, s11, 5
	s_mov_b64 s[2:3], 0

;     __host__ __device__ bool next(int i, Unit& u) const {
;         const long L = (long)i * G + c; if (L >= nwg) return false;
;         int wgid = (int)L; { const int q = nwg / NXCD, r = nwg % NXCD, xcd = wgid % NXCD, off = wgid / NXCD; wgid = (xcd < r ? xcd * (q + 1) : r * (q + 1) + (xcd - r) * q) + off; }
; template <class Epi, class Sched, bool ALIGN_EPI = false, bool SP2 = false>
; __device__ __forceinline__ void gemm_phase(PG8_LAS unsigned char* lds, const Gemm g, const Sched& S, const Epi& E, const int tid) {
;     ...
;         const bool has_next = S.next(ui + 1, nxt);
.LBB0_781:
	s_add_i32 s52, s52, 1
	s_mul_i32 s1, s52, s53
	s_mul_hi_u32 s6, s52, s87
	s_add_i32 s1, s6, s1
	s_mul_i32 s6, s52, s87
	s_add_u32 s6, s6, s86
	s_addc_u32 s7, s1, s54
	s_waitcnt lgkmcnt(0)
	v_mov_b64_e32 v[6:7], 0x100
	v_mov_b64_e32 v[162:163], 0xff
	v_cmp_gt_i64_e32 vcc, s[6:7], v[162:163]
	v_cmp_lt_i64_e64 s[8:9], s[6:7], v[6:7]
	s_cbranch_vccnz .LBB0_787
	s_ashr_i32 s1, s6, 31
	s_lshr_b32 s1, s1, 29
	s_add_i32 s1, s6, s1
	s_and_b32 s7, s1, -8
	s_sub_i32 s14, s6, s7
	s_cmp_gt_i32 s14, -1
	s_mov_b64 s[6:7], -1
	s_cbranch_scc0 .LBB0_784
	s_lshl_b32 s15, s14, 5
	s_mov_b64 s[6:7], 0

	.amdhsa_kernel _Z8mega_fwd3Ctx
		.amdhsa_group_segment_fixed_size 0
		.amdhsa_private_segment_fixed_size 0
		.amdhsa_kernarg_size 416
		.amdhsa_user_sgpr_count 2
		.amdhsa_user_sgpr_dispatch_ptr 0
		.amdhsa_user_sgpr_queue_ptr 0
		.amdhsa_user_sgpr_kernarg_segment_ptr 1
		.amdhsa_user_sgpr_dispatch_id 0
		.amdhsa_user_sgpr_kernarg_preload_length 0
		.amdhsa_user_sgpr_kernarg_preload_offset 0
		.amdhsa_user_sgpr_private_segment_size 0
		.amdhsa_uses_dynamic_stack 0
		.amdhsa_enable_private_segment 0
		.amdhsa_system_sgpr_workgroup_id_x 1
		.amdhsa_system_sgpr_workgroup_id_y 0
		.amdhsa_system_sgpr_workgroup_id_z 0
		.amdhsa_system_sgpr_workgroup_info 0
		.amdhsa_system_vgpr_workitem_id 2
		.amdhsa_next_free_vgpr 256
		.amdhsa_next_free_sgpr 102
		.amdhsa_accum_offset 256
		.amdhsa_reserve_vcc 1
		.amdhsa_float_round_mode_32 0
		.amdhsa_float_round_mode_16_64 0
		.amdhsa_float_denorm_mode_32 3
		.amdhsa_float_denorm_mode_16_64 3
		.amdhsa_dx10_clamp 1
		.amdhsa_ieee_mode 1
		.amdhsa_fp16_overflow 0
		.amdhsa_tg_split 0
		.amdhsa_exception_fp_ieee_invalid_op 0
		.amdhsa_exception_fp_denorm_src 0
		.amdhsa_exception_fp_ieee_div_zero 0
		.amdhsa_exception_fp_ieee_overflow 0
		.amdhsa_exception_fp_ieee_underflow 0
		.amdhsa_exception_fp_ieee_inexact 0
		.amdhsa_exception_int_div_zero 0
	.end_amdhsa_kernel

amdhsa.kernels:
  - .agpr_count:     0
    .args:
      - .offset:         0
        .size:           160
        .value_kind:     by_value
      - .offset:         160
        .size:           4
        .value_kind:     hidden_block_count_x
      - .offset:         164
        .size:           4
        .value_kind:     hidden_block_count_y
      - .offset:         168
        .size:           4
        .value_kind:     hidden_block_count_z
      - .offset:         172
        .size:           2
        .value_kind:     hidden_group_size_x
      - .offset:         174
        .size:           2
        .value_kind:     hidden_group_size_y
      - .offset:         176
        .size:           2
        .value_kind:     hidden_group_size_z
      - .offset:         178
        .size:           2
        .value_kind:     hidden_remainder_x
      - .offset:         180
        .size:           2
        .value_kind:     hidden_remainder_y
      - .offset:         182
        .size:           2
        .value_kind:     hidden_remainder_z
      - .offset:         200
        .size:           8
        .value_kind:     hidden_global_offset_x
      - .offset:         208
        .size:           8
        .value_kind:     hidden_global_offset_y
      - .offset:         216
        .size:           8
        .value_kind:     hidden_global_offset_z
      - .offset:         224
        .size:           2
        .value_kind:     hidden_grid_dims
      - .offset:         248
        .size:           8
        .value_kind:     hidden_multigrid_sync_arg
      - .offset:         280
        .size:           4
        .value_kind:     hidden_dynamic_lds_size
    .group_segment_fixed_size: 0
    .kernarg_segment_align: 8
    .kernarg_segment_size: 416
    .language:       OpenCL C
    .language_version:
      - 2
      - 0
    .max_flat_workgroup_size: 512
    .name:           _Z8mega_fwd3Ctx
    .private_segment_fixed_size: 0
    .sgpr_count:     108
    .sgpr_spill_count: 211
    .symbol:         _Z8mega_fwd3Ctx.kd
    .uniform_work_group_size: 1
    .uses_dynamic_stack: false
    .vgpr_count:     256
    .vgpr_spill_count: 0
    .wavefront_size: 64
